# GLA pass-1 (chain<0>, now the mid-P2 barrier pole) state-update step software-pipelined through a VGPR ring; plus LN1/LN2 load hoist, deferred sample units, batched fold
# speedup vs baseline: 1.0075x; 1.0075x over previous
; #define GLDS __attribute__((address_space(3)))
; __device__ __forceinline__ s16x4 trrd(ldsp p) { typedef short v4s __attribute__((ext_vector_type(4))); return __builtin_bit_cast(s16x4, __builtin_amdgcn_ds_read_tr16_b64_v4i16((GLDS v4s*)p)); }
; template <int MODE> __device__ __forceinline__ void chain(int b, int h, int seg, float* __restrict__ SLOC, float* __restrict__ DTOT, const bf16_t* __restrict__ QB, const bf16_t* __restrict__ KB, const bf16_t* __restrict__ VB, bf16_t* __restrict__ OB, const bf16_t* __restrict__ RB, const float* __res ...
;     ...
;         for (int ks = 0; ks < 4; ++ks) { const s16x4 lo = trrd(vtr0 + ks * 16 * V_RS), hh = trrd(vtr0 + ks * 16 * V_RS + 4 * V_RS); vf[ks] = (bf16x8){lo[0], lo[1], lo[2], lo[3], hh[0], hh[1], hh[2], hh[3]}; }
;     ...
; #pragma unroll
;         for (int cb = 0; cb < 4; ++cb) {
; #pragma unroll
;             for (int g = 0; g < 4; ++g) { const f32x4 e = *(const GLDS f32x4*)(EBL + 32 * cb + 8 * g + 4 * hi);
;                 S[cb][4 * g] *= e[0]; S[cb][4 * g + 1] *= e[1]; S[cb][4 * g + 2] *= e[2]; S[cb][4 * g + 3] *= e[3]; }
; #pragma unroll
;             for (int ks = 0; ks < 4; ++ks) { const bf16x8 kf = *(const GLDS bf16x8*)(L + KH_OFF + (32 * cb + r32) * KH_RS + (16 * ks + 8 * hi) * 2);
;                 S[cb] = __builtin_amdgcn_mfma_f32_32x32x16_bf16(kf, vf[ks], S[cb], 0, 0, 0); }
;             __builtin_amdgcn_sched_barrier(0);
;         }
.LBB0_487:
	s_waitcnt lgkmcnt(0)
	s_barrier
	v_add_u32_e32 v135, 0x19400, v128
	ds_read_b128 v[136:139], v135
	ds_read_b128 v[140:143], v135 offset:32
	ds_read_b128 v[144:147], v135 offset:64
	ds_read_b128 v[148:151], v135 offset:96
	ds_read_b64_tr_b16 v[82:83], v122 offset:53248
	ds_read_b64_tr_b16 v[84:85], v122 offset:55552
	ds_read_b128 v[152:155], v134 offset:34816
	ds_read_b64_tr_b16 v[86:87], v122 offset:62464
	ds_read_b64_tr_b16 v[88:89], v122 offset:64768
	ds_read_b128 v[156:159], v134 offset:34848
	ds_read_b64_tr_b16 v[94:95], v123 offset:18432
	ds_read_b64_tr_b16 v[96:97], v123 offset:20736
	s_waitcnt lgkmcnt(11)
	v_pk_mul_f32 v[50:51], v[50:51], v[136:137]
	v_pk_mul_f32 v[52:53], v[52:53], v[138:139]
	ds_read_b128 v[160:163], v134 offset:34880
	s_waitcnt lgkmcnt(11)
	v_pk_mul_f32 v[54:55], v[54:55], v[140:141]
	v_pk_mul_f32 v[56:57], v[56:57], v[142:143]
	ds_read_b64_tr_b16 v[90:91], v123 offset:27648
	s_waitcnt lgkmcnt(11)
	v_pk_mul_f32 v[58:59], v[58:59], v[144:145]
	v_pk_mul_f32 v[60:61], v[60:61], v[146:147]
	ds_read_b64_tr_b16 v[92:93], v123 offset:29952
	s_waitcnt lgkmcnt(11)
	v_pk_mul_f32 v[62:63], v[62:63], v[148:149]
	v_pk_mul_f32 v[64:65], v[64:65], v[150:151]
	ds_read_b128 v[164:167], v134 offset:34912
	s_waitcnt lgkmcnt(9)
	s_nop 1
	v_mfma_f32_32x32x16_bf16 v[50:65], v[152:155], v[82:85], v[50:65]
	ds_read_b128 v[168:171], v135 offset:128
	ds_read_b128 v[172:175], v135 offset:160
	ds_read_b128 v[176:179], v135 offset:192
	v_add_f32_e64 v104, v104, v108
	v_add_f32_e64 v105, v105, v109
	s_waitcnt lgkmcnt(9)
	v_mfma_f32_32x32x16_bf16 v[50:65], v[156:159], v[86:89], v[50:65]
	ds_read_b128 v[136:139], v135 offset:224
	ds_read_b128 v[140:143], v134 offset:39424
	ds_read_b128 v[144:147], v134 offset:39456
	s_waitcnt lgkmcnt(9)
	v_mfma_f32_32x32x16_bf16 v[50:65], v[160:163], v[94:97], v[50:65]
	ds_read_b128 v[148:151], v134 offset:39488
	ds_read_b128 v[152:155], v134 offset:39520
	ds_read_b128 v[156:159], v135 offset:256
	s_waitcnt lgkmcnt(9)
	v_mfma_f32_32x32x16_bf16 v[50:65], v[164:167], v[90:93], v[50:65]
	ds_read_b128 v[160:163], v135 offset:288
	ds_read_b128 v[164:167], v135 offset:320
	s_waitcnt lgkmcnt(10)
	v_pk_mul_f32 v[34:35], v[34:35], v[168:169]
	v_pk_mul_f32 v[36:37], v[36:37], v[170:171]
	ds_read_b128 v[168:171], v135 offset:352
	s_waitcnt lgkmcnt(10)
	v_pk_mul_f32 v[38:39], v[38:39], v[172:173]
	v_pk_mul_f32 v[40:41], v[40:41], v[174:175]
	ds_read_b128 v[172:175], v134 offset:44032
	s_waitcnt lgkmcnt(10)
	v_pk_mul_f32 v[42:43], v[42:43], v[176:177]
	v_pk_mul_f32 v[44:45], v[44:45], v[178:179]
	ds_read_b128 v[176:179], v134 offset:44064
	s_waitcnt lgkmcnt(10)
	v_pk_mul_f32 v[46:47], v[46:47], v[136:137]
	v_pk_mul_f32 v[48:49], v[48:49], v[138:139]
	ds_read_b128 v[136:139], v134 offset:44096
	s_waitcnt lgkmcnt(10)
	s_nop 1
	v_mfma_f32_32x32x16_bf16 v[34:49], v[140:143], v[82:85], v[34:49]
	ds_read_b128 v[140:143], v134 offset:44128
	s_waitcnt lgkmcnt(10)
	v_mfma_f32_32x32x16_bf16 v[34:49], v[144:147], v[86:89], v[34:49]
	ds_read_b128 v[144:147], v135 offset:384
	s_waitcnt lgkmcnt(10)
	v_mfma_f32_32x32x16_bf16 v[34:49], v[148:151], v[94:97], v[34:49]
	ds_read_b128 v[148:151], v135 offset:416
	s_waitcnt lgkmcnt(10)
	v_mfma_f32_32x32x16_bf16 v[34:49], v[152:155], v[90:93], v[34:49]
	ds_read_b128 v[152:155], v135 offset:448
	s_waitcnt lgkmcnt(10)
	v_pk_mul_f32 v[18:19], v[18:19], v[156:157]
	v_pk_mul_f32 v[20:21], v[20:21], v[158:159]
	ds_read_b128 v[156:159], v135 offset:480
	s_waitcnt lgkmcnt(10)
	v_pk_mul_f32 v[22:23], v[22:23], v[160:161]
	v_pk_mul_f32 v[24:25], v[24:25], v[162:163]
	ds_read_b128 v[160:163], v134 offset:48640
	s_waitcnt lgkmcnt(10)
	v_pk_mul_f32 v[26:27], v[26:27], v[164:165]
	v_pk_mul_f32 v[28:29], v[28:29], v[166:167]
	ds_read_b128 v[164:167], v134 offset:48672
	s_waitcnt lgkmcnt(10)
	v_pk_mul_f32 v[30:31], v[30:31], v[168:169]
	v_pk_mul_f32 v[32:33], v[32:33], v[170:171]
	ds_read_b128 v[168:171], v134 offset:48704
	s_waitcnt lgkmcnt(10)
	s_nop 1
	v_mfma_f32_32x32x16_bf16 v[18:33], v[172:175], v[82:85], v[18:33]
	ds_read_b128 v[172:175], v134 offset:48736
	s_waitcnt lgkmcnt(10)
	v_mfma_f32_32x32x16_bf16 v[18:33], v[176:179], v[86:89], v[18:33]
	s_waitcnt lgkmcnt(9)
	v_mfma_f32_32x32x16_bf16 v[18:33], v[136:139], v[94:97], v[18:33]
	s_waitcnt lgkmcnt(8)
	v_mfma_f32_32x32x16_bf16 v[18:33], v[140:143], v[90:93], v[18:33]
	s_waitcnt lgkmcnt(7)
	v_pk_mul_f32 v[2:3], v[2:3], v[144:145]
	v_pk_mul_f32 v[4:5], v[4:5], v[146:147]
	s_waitcnt lgkmcnt(6)
	v_pk_mul_f32 v[6:7], v[6:7], v[148:149]
	v_pk_mul_f32 v[8:9], v[8:9], v[150:151]
	s_waitcnt lgkmcnt(5)
	v_pk_mul_f32 v[10:11], v[10:11], v[152:153]
	v_pk_mul_f32 v[12:13], v[12:13], v[154:155]
	s_waitcnt lgkmcnt(4)
	v_pk_mul_f32 v[14:15], v[14:15], v[156:157]
	v_pk_mul_f32 v[16:17], v[16:17], v[158:159]
	s_waitcnt lgkmcnt(3)
	s_nop 1
	v_mfma_f32_32x32x16_bf16 v[2:17], v[160:163], v[82:85], v[2:17]
	s_waitcnt lgkmcnt(2)
	v_mfma_f32_32x32x16_bf16 v[2:17], v[164:167], v[86:89], v[2:17]
	s_waitcnt lgkmcnt(1)
	v_mfma_f32_32x32x16_bf16 v[2:17], v[168:171], v[94:97], v[2:17]
	s_waitcnt lgkmcnt(0)
	v_mfma_f32_32x32x16_bf16 v[2:17], v[172:175], v[90:93], v[2:17]
	s_add_u32 s82, s82, 0x20000
	s_addc_u32 s83, s83, 0
	s_add_u32 s78, s78, 0x1000
	s_addc_u32 s79, s79, 0
	s_add_u32 s80, s80, 0x10000
	s_waitcnt lgkmcnt(0)
	s_barrier
	s_addc_u32 s81, s81, 0
	s_cmp_eq_u32 s82, 0x200000
	s_cbranch_scc1 .LBB0_492
